# grid barrier: the 16th arriver of each XCC issues an early L2 write-back so the last arriver's write-back has less to flush
# speedup vs baseline: 1.0027x; 1.0015x over previous
; __device__ __forceinline__ void grid_barrier(unsigned* ctr, unsigned target) {
;     asm volatile("s_waitcnt vmcnt(0)" ::: "memory");
;     __syncthreads();
;     if (threadIdx.x == 0) {
;         __builtin_amdgcn_fence(__ATOMIC_RELEASE, "agent");
;         asm volatile("s_waitcnt vmcnt(0)" ::: "memory");
;         __hip_atomic_fetch_add(ctr, 1u, __ATOMIC_RELAXED, __HIP_MEMORY_SCOPE_AGENT);
;         unsigned spins = 0;
;         while (__hip_atomic_load(ctr, __ATOMIC_RELAXED, __HIP_MEMORY_SCOPE_AGENT) < target) { __builtin_amdgcn_s_sleep(2); if (++spins > (1u << 24)) break; }
;         __builtin_amdgcn_fence(__ATOMIC_ACQUIRE, "agent");
;         asm volatile("s_waitcnt vmcnt(0)" ::: "memory");
;     }
;     __syncthreads();
; }
.Lmy_gb1_follow:
	s_cmp_lg_u32 s7, 16
	s_cbranch_scc1 .Lmy_gb1_nopre
	buffer_wbl2 sc1

; __device__ __forceinline__ void grid_barrier(unsigned* ctr, unsigned target) {
;     asm volatile("s_waitcnt vmcnt(0)" ::: "memory");
;     __syncthreads();
;     if (threadIdx.x == 0) {
;         __builtin_amdgcn_fence(__ATOMIC_RELEASE, "agent");
;         asm volatile("s_waitcnt vmcnt(0)" ::: "memory");
;         __hip_atomic_fetch_add(ctr, 1u, __ATOMIC_RELAXED, __HIP_MEMORY_SCOPE_AGENT);
;         unsigned spins = 0;
;         while (__hip_atomic_load(ctr, __ATOMIC_RELAXED, __HIP_MEMORY_SCOPE_AGENT) < target) { __builtin_amdgcn_s_sleep(2); if (++spins > (1u << 24)) break; }
;         __builtin_amdgcn_fence(__ATOMIC_ACQUIRE, "agent");
;         asm volatile("s_waitcnt vmcnt(0)" ::: "memory");
;     }
;     __syncthreads();
; }
.Lmy_gb2_follow:
	s_cmp_lg_u32 s7, 48
	s_cbranch_scc1 .Lmy_gb2_nopre
	buffer_wbl2 sc1

; __device__ __forceinline__ void grid_barrier(unsigned* ctr, unsigned target) {
;     asm volatile("s_waitcnt vmcnt(0)" ::: "memory");
;     __syncthreads();
;     if (threadIdx.x == 0) {
;         __builtin_amdgcn_fence(__ATOMIC_RELEASE, "agent");
;         asm volatile("s_waitcnt vmcnt(0)" ::: "memory");
;         __hip_atomic_fetch_add(ctr, 1u, __ATOMIC_RELAXED, __HIP_MEMORY_SCOPE_AGENT);
;         unsigned spins = 0;
;         while (__hip_atomic_load(ctr, __ATOMIC_RELAXED, __HIP_MEMORY_SCOPE_AGENT) < target) { __builtin_amdgcn_s_sleep(2); if (++spins > (1u << 24)) break; }
;         __builtin_amdgcn_fence(__ATOMIC_ACQUIRE, "agent");
;         asm volatile("s_waitcnt vmcnt(0)" ::: "memory");
;     }
;     __syncthreads();
; }
.Lmy_gb3_follow:
	s_cmp_lg_u32 s7, 80
	s_cbranch_scc1 .Lmy_gb3_nopre
	buffer_wbl2 sc1

; __device__ __forceinline__ void grid_barrier(unsigned* ctr, unsigned target) {
;     asm volatile("s_waitcnt vmcnt(0)" ::: "memory");
;     __syncthreads();
;     if (threadIdx.x == 0) {
;         __builtin_amdgcn_fence(__ATOMIC_RELEASE, "agent");
;         asm volatile("s_waitcnt vmcnt(0)" ::: "memory");
;         __hip_atomic_fetch_add(ctr, 1u, __ATOMIC_RELAXED, __HIP_MEMORY_SCOPE_AGENT);
;         unsigned spins = 0;
;         while (__hip_atomic_load(ctr, __ATOMIC_RELAXED, __HIP_MEMORY_SCOPE_AGENT) < target) { __builtin_amdgcn_s_sleep(2); if (++spins > (1u << 24)) break; }
;         __builtin_amdgcn_fence(__ATOMIC_ACQUIRE, "agent");
;         asm volatile("s_waitcnt vmcnt(0)" ::: "memory");
;     }
;     __syncthreads();
; }
.Lmy_gb4_follow:
	s_cmp_lg_u32 s5, 112
	s_cbranch_scc1 .Lmy_gb4_nopre
	buffer_wbl2 sc1

; __device__ __forceinline__ void grid_barrier(unsigned* ctr, unsigned target) {
;     asm volatile("s_waitcnt vmcnt(0)" ::: "memory");
;     __syncthreads();
;     if (threadIdx.x == 0) {
;         __builtin_amdgcn_fence(__ATOMIC_RELEASE, "agent");
;         asm volatile("s_waitcnt vmcnt(0)" ::: "memory");
;         __hip_atomic_fetch_add(ctr, 1u, __ATOMIC_RELAXED, __HIP_MEMORY_SCOPE_AGENT);
;         unsigned spins = 0;
;         while (__hip_atomic_load(ctr, __ATOMIC_RELAXED, __HIP_MEMORY_SCOPE_AGENT) < target) { __builtin_amdgcn_s_sleep(2); if (++spins > (1u << 24)) break; }
;         __builtin_amdgcn_fence(__ATOMIC_ACQUIRE, "agent");
;         asm volatile("s_waitcnt vmcnt(0)" ::: "memory");
;     }
;     __syncthreads();
; }
.Lmy_gb5_follow:
	s_cmp_lg_u32 s5, 144
	s_cbranch_scc1 .Lmy_gb5_nopre
	buffer_wbl2 sc1

; __device__ __forceinline__ void grid_barrier(unsigned* ctr, unsigned target) {
;     asm volatile("s_waitcnt vmcnt(0)" ::: "memory");
;     __syncthreads();
;     if (threadIdx.x == 0) {
;         __builtin_amdgcn_fence(__ATOMIC_RELEASE, "agent");
;         asm volatile("s_waitcnt vmcnt(0)" ::: "memory");
;         __hip_atomic_fetch_add(ctr, 1u, __ATOMIC_RELAXED, __HIP_MEMORY_SCOPE_AGENT);
;         unsigned spins = 0;
;         while (__hip_atomic_load(ctr, __ATOMIC_RELAXED, __HIP_MEMORY_SCOPE_AGENT) < target) { __builtin_amdgcn_s_sleep(2); if (++spins > (1u << 24)) break; }
;         __builtin_amdgcn_fence(__ATOMIC_ACQUIRE, "agent");
;         asm volatile("s_waitcnt vmcnt(0)" ::: "memory");
;     }
;     __syncthreads();
; }
.Lmy_gb6_follow:
	s_cmp_lg_u32 s7, 176
	s_cbranch_scc1 .Lmy_gb6_nopre
	buffer_wbl2 sc1

; __device__ __forceinline__ void grid_barrier(unsigned* ctr, unsigned target) {
;     asm volatile("s_waitcnt vmcnt(0)" ::: "memory");
;     __syncthreads();
;     if (threadIdx.x == 0) {
;         __builtin_amdgcn_fence(__ATOMIC_RELEASE, "agent");
;         asm volatile("s_waitcnt vmcnt(0)" ::: "memory");
;         __hip_atomic_fetch_add(ctr, 1u, __ATOMIC_RELAXED, __HIP_MEMORY_SCOPE_AGENT);
;         unsigned spins = 0;
;         while (__hip_atomic_load(ctr, __ATOMIC_RELAXED, __HIP_MEMORY_SCOPE_AGENT) < target) { __builtin_amdgcn_s_sleep(2); if (++spins > (1u << 24)) break; }
;         __builtin_amdgcn_fence(__ATOMIC_ACQUIRE, "agent");
;         asm volatile("s_waitcnt vmcnt(0)" ::: "memory");
;     }
;     __syncthreads();
; }
.Lmy_gb7_follow:
	s_cmp_lg_u32 s5, 208
	s_cbranch_scc1 .Lmy_gb7_nopre
	buffer_wbl2 sc1
